# P0 log-decay loop: ln(y)*log2e folded to log2(y), dead libm range handling removed (same v_exp/v_log f32); F1: LDS chunk swizzle vs ds_read_b128 lane groups, double-buffered store staging (one barrier
# speedup vs baseline: 1.0562x; 1.0116x over previous
.LBB0_22:
	v_mul_u32_u24_e32 v34, 0x2880, v0
	v_mov_b32_e32 v35, 0
	s_waitcnt lgkmcnt(0)
	v_lshl_add_u64 v[22:23], s[38:39], 0, v[34:35]
	s_mov_b64 s[4:5], 0x1000
	v_lshl_add_u64 v[14:15], v[22:23], 0, s[4:5]
	v_add_co_u32_e32 v18, vcc, 0x1000, v22
	s_barrier
	global_load_dwordx4 v[2:5], v[14:15], off offset:16
	global_load_dwordx4 v[6:9], v[14:15], off offset:32
	v_addc_co_u32_e32 v19, vcc, 0, v23, vcc
	global_load_dwordx4 v[10:13], v[18:19], off
	s_nop 0
	global_load_dwordx4 v[14:17], v[14:15], off offset:48
	s_nop 0
	global_load_dwordx4 v[18:21], v[18:19], off offset:64
	s_mov_b64 s[0:1], 0x1040
	v_lshl_add_u64 v[30:31], v[22:23], 0, s[0:1]
	global_load_dwordx4 v[22:25], v[30:31], off offset:16
	global_load_dwordx4 v[26:29], v[30:31], off offset:48
	s_nop 0
	global_load_dwordx4 v[30:33], v[30:31], off offset:32
	v_or_b32_e32 v54, 0x200, v0
	v_mul_u32_u24_e32 v34, 0x2880, v54
	s_movk_i32 s7, 0x1000
	v_lshl_add_u64 v[48:49], s[38:39], 0, v[34:35]
	v_add_co_u32_e32 v52, vcc, s7, v48
	v_lshl_add_u64 v[50:51], v[48:49], 0, s[4:5]
	s_nop 0
	v_addc_co_u32_e32 v53, vcc, 0, v49, vcc
	global_load_dwordx4 v[36:39], v[52:53], off
	global_load_dwordx4 v[40:43], v[50:51], off offset:32
	global_load_dwordx4 v[44:47], v[50:51], off offset:16
	s_movk_i32 s6, 0x7fff
	v_lshl_add_u32 v1, v0, 1, 0
	s_cmpk_lt_i32 s80, 0x1000
	s_waitcnt vmcnt(10)
	v_bfe_u32 v34, v2, 16, 1
	v_bfe_u32 v57, v5, 16, 1
	v_bfe_u32 v55, v3, 16, 1
	v_bfe_u32 v56, v4, 16, 1
	s_waitcnt vmcnt(9)
	v_bfe_u32 v58, v6, 16, 1
	v_bfe_u32 v59, v7, 16, 1
	v_bfe_u32 v60, v8, 16, 1
	v_bfe_u32 v61, v9, 16, 1
	s_waitcnt vmcnt(8)
	v_bfe_u32 v62, v10, 16, 1
	v_add3_u32 v2, v2, v34, s6
	v_add3_u32 v5, v5, v57, s6
	s_waitcnt vmcnt(7)
	v_bfe_u32 v57, v14, 16, 1
	v_add3_u32 v3, v3, v55, s6
	v_add3_u32 v4, v4, v56, s6
	v_bfe_u32 v34, v11, 16, 1
	v_bfe_u32 v55, v12, 16, 1
	v_bfe_u32 v56, v13, 16, 1
	v_add3_u32 v6, v6, v58, s6
	v_add3_u32 v7, v7, v59, s6
	v_add3_u32 v8, v8, v60, s6
	v_add3_u32 v9, v9, v61, s6
	v_bfe_u32 v58, v15, 16, 1
	v_bfe_u32 v59, v16, 16, 1
	v_bfe_u32 v60, v17, 16, 1
	v_add3_u32 v10, v10, v62, s6
	ds_write_b16_d16_hi v1, v2 offset:8256
	ds_write_b16_d16_hi v1, v3 offset:10320
	ds_write_b16_d16_hi v1, v4 offset:12384
	ds_write_b16_d16_hi v1, v5 offset:14448
	ds_write_b16_d16_hi v1, v6 offset:16512
	ds_write_b16_d16_hi v1, v7 offset:18576
	ds_write_b16_d16_hi v1, v8 offset:20640
	ds_write_b16_d16_hi v1, v9 offset:22704
	v_add3_u32 v2, v14, v57, s6
	v_add3_u32 v11, v11, v34, s6
	v_add3_u32 v12, v12, v55, s6
	v_add3_u32 v13, v13, v56, s6
	v_add3_u32 v3, v15, v58, s6
	v_add3_u32 v4, v16, v59, s6
	v_add3_u32 v5, v17, v60, s6
	ds_write_b16_d16_hi v1, v10
	ds_write_b16_d16_hi v1, v11 offset:2064
	ds_write_b16_d16_hi v1, v12 offset:4128
	ds_write_b16_d16_hi v1, v13 offset:6192
	ds_write_b16_d16_hi v1, v2 offset:24768
	ds_write_b16_d16_hi v1, v3 offset:26832
	ds_write_b16_d16_hi v1, v4 offset:28896
	ds_write_b16_d16_hi v1, v5 offset:30960
	s_waitcnt vmcnt(6)
	v_bfe_u32 v2, v18, 16, 1
	v_add3_u32 v2, v18, v2, s6
	ds_write_b16_d16_hi v1, v2 offset:33024
	v_bfe_u32 v2, v19, 16, 1
	v_add3_u32 v2, v19, v2, s6
	ds_write_b16_d16_hi v1, v2 offset:35088
	v_bfe_u32 v2, v20, 16, 1
	v_add3_u32 v2, v20, v2, s6
	ds_write_b16_d16_hi v1, v2 offset:37152
	v_bfe_u32 v2, v21, 16, 1
	v_add3_u32 v6, v21, v2, s6
	global_load_dwordx4 v[2:5], v[50:51], off offset:48
	s_waitcnt vmcnt(6)
	v_bfe_u32 v10, v25, 16, 1
	v_add3_u32 v10, v25, v10, s6
	ds_write_b16_d16_hi v1, v10 offset:47472
	s_waitcnt vmcnt(4)
	v_bfe_u32 v10, v30, 16, 1
	v_add3_u32 v10, v30, v10, s6
	ds_write_b16_d16_hi v1, v10 offset:49536
	v_bfe_u32 v10, v31, 16, 1
	v_add3_u32 v10, v31, v10, s6
	ds_write_b16_d16_hi v1, v10 offset:51600
	v_bfe_u32 v10, v32, 16, 1
	v_add3_u32 v10, v32, v10, s6
	ds_write_b16_d16_hi v1, v10 offset:53664
	v_bfe_u32 v10, v33, 16, 1
	v_add3_u32 v10, v33, v10, s6
	ds_write_b16_d16_hi v1, v10 offset:55728
	v_bfe_u32 v10, v26, 16, 1
	v_add3_u32 v10, v26, v10, s6
	ds_write_b16_d16_hi v1, v6 offset:39216
	v_bfe_u32 v6, v22, 16, 1
	ds_write_b16_d16_hi v1, v10 offset:57792
	v_bfe_u32 v10, v27, 16, 1
	v_add3_u32 v6, v22, v6, s6
	v_add3_u32 v10, v27, v10, s6
	ds_write_b16_d16_hi v1, v6 offset:41280
	v_bfe_u32 v6, v23, 16, 1
	ds_write_b16_d16_hi v1, v10 offset:59856
	v_bfe_u32 v10, v28, 16, 1
	v_add3_u32 v6, v23, v6, s6
	v_add3_u32 v10, v28, v10, s6
	ds_write_b16_d16_hi v1, v6 offset:43344
	v_bfe_u32 v6, v24, 16, 1
	ds_write_b16_d16_hi v1, v10 offset:61920
	v_bfe_u32 v10, v29, 16, 1
	v_add3_u32 v6, v24, v6, s6
	v_add3_u32 v10, v29, v10, s6
	ds_write_b16_d16_hi v1, v6 offset:45408
	ds_write_b16_d16_hi v1, v10 offset:63984
	v_lshl_add_u64 v[22:23], v[48:49], 0, s[0:1]
	global_load_dwordx4 v[6:9], v[52:53], off offset:64
	global_load_dwordx4 v[10:13], v[22:23], off offset:48
	global_load_dwordx4 v[14:17], v[22:23], off offset:32
	global_load_dwordx4 v[18:21], v[22:23], off offset:16
	s_waitcnt vmcnt(7)
	v_bfe_u32 v22, v36, 16, 1
	v_lshl_add_u32 v1, v54, 1, 0
	v_add3_u32 v22, v36, v22, s6
	ds_write_b16_d16_hi v1, v22
	v_bfe_u32 v22, v37, 16, 1
	v_add3_u32 v22, v37, v22, s6
	ds_write_b16_d16_hi v1, v22 offset:2064
	v_bfe_u32 v22, v38, 16, 1
	v_add3_u32 v22, v38, v22, s6
	ds_write_b16_d16_hi v1, v22 offset:4128
	v_bfe_u32 v22, v39, 16, 1
	v_add3_u32 v22, v39, v22, s6
	ds_write_b16_d16_hi v1, v22 offset:6192
	s_waitcnt vmcnt(5)
	v_bfe_u32 v22, v44, 16, 1
	v_add3_u32 v22, v44, v22, s6
	ds_write_b16_d16_hi v1, v22 offset:8256
	v_bfe_u32 v22, v45, 16, 1
	v_add3_u32 v22, v45, v22, s6
	ds_write_b16_d16_hi v1, v22 offset:10320
	v_bfe_u32 v22, v46, 16, 1
	v_add3_u32 v22, v46, v22, s6
	ds_write_b16_d16_hi v1, v22 offset:12384
	v_bfe_u32 v22, v47, 16, 1
	v_add3_u32 v22, v47, v22, s6
	ds_write_b16_d16_hi v1, v22 offset:14448
	v_bfe_u32 v22, v40, 16, 1
	v_add3_u32 v22, v40, v22, s6
	ds_write_b16_d16_hi v1, v22 offset:16512
	v_bfe_u32 v22, v41, 16, 1
	v_add3_u32 v22, v41, v22, s6
	ds_write_b16_d16_hi v1, v22 offset:18576
	v_bfe_u32 v22, v42, 16, 1
	v_add3_u32 v22, v42, v22, s6
	ds_write_b16_d16_hi v1, v22 offset:20640
	v_bfe_u32 v22, v43, 16, 1
	v_add3_u32 v22, v43, v22, s6
	ds_write_b16_d16_hi v1, v22 offset:22704
	s_movk_i32 s0, 0x100
	v_cmp_gt_u32_e32 vcc, s0, v0
	s_waitcnt vmcnt(4)
	v_bfe_u32 v22, v2, 16, 1
	v_add3_u32 v2, v2, v22, s6
	ds_write_b16_d16_hi v1, v2 offset:24768
	v_bfe_u32 v2, v3, 16, 1
	v_add3_u32 v2, v3, v2, s6
	ds_write_b16_d16_hi v1, v2 offset:26832
	v_bfe_u32 v2, v4, 16, 1
	v_add3_u32 v2, v4, v2, s6
	ds_write_b16_d16_hi v1, v2 offset:28896
	v_bfe_u32 v2, v5, 16, 1
	v_add3_u32 v2, v5, v2, s6
	ds_write_b16_d16_hi v1, v2 offset:30960
	v_mov_b32_e32 v2, s45
	v_mov_b32_e32 v3, s41
	v_cndmask_b32_e32 v3, v2, v3, vcc
	v_mov_b32_e32 v2, s44
	v_mov_b32_e32 v4, s40
	v_cndmask_b32_e32 v2, v2, v4, vcc
	v_mov_b32_e32 v4, 2
	v_lshlrev_b32_sdwa v34, v4, v0 dst_sel:DWORD dst_unused:UNUSED_PAD src0_sel:DWORD src1_sel:BYTE_0
	v_lshl_add_u64 v[2:3], v[2:3], 0, v[34:35]
	v_add_co_u32_e64 v4, s[0:1], s7, v2
	global_load_dword v25, v[2:3], off
	global_load_dword v26, v[2:3], off offset:1024
	global_load_dword v27, v[2:3], off offset:2048
	global_load_dword v28, v[2:3], off offset:3072
	v_addc_co_u32_e64 v5, s[0:1], 0, v3, s[0:1]
	s_movk_i32 s0, 0x2000
	s_nop 0
	v_add_co_u32_e64 v22, s[0:1], s0, v2
	s_waitcnt vmcnt(7)
	v_bfe_u32 v24, v6, 16, 1
	v_addc_co_u32_e64 v23, s[0:1], 0, v3, s[0:1]
	s_movk_i32 s0, 0x3000
	s_nop 0
	v_add_co_u32_e64 v2, s[0:1], s0, v2
	global_load_dword v29, v[22:23], off offset:-4096
	global_load_dword v30, v[4:5], off offset:1024
	global_load_dword v31, v[4:5], off offset:2048
	global_load_dword v32, v[4:5], off offset:3072
	global_load_dword v33, v[22:23], off
	global_load_dword v36, v[22:23], off offset:1024
	global_load_dword v37, v[22:23], off offset:2048
	global_load_dword v38, v[22:23], off offset:3072
	v_addc_co_u32_e64 v3, s[0:1], 0, v3, s[0:1]
	global_load_dword v22, v[2:3], off
	global_load_dword v23, v[2:3], off offset:1024
	global_load_dword v39, v[2:3], off offset:2048
	global_load_dword v40, v[2:3], off offset:3072
	v_mov_b32_e32 v2, s47
	v_mov_b32_e32 v3, s43
	v_cndmask_b32_e32 v3, v2, v3, vcc
	v_mov_b32_e32 v2, s46
	v_mov_b32_e32 v4, s42
	v_cndmask_b32_e32 v2, v2, v4, vcc
	v_lshl_add_u64 v[2:3], v[2:3], 0, v[34:35]
	global_load_dword v34, v[2:3], off
	v_add3_u32 v2, v6, v24, s6
	ds_write_b16_d16_hi v1, v2 offset:33024
	v_bfe_u32 v2, v7, 16, 1
	v_add3_u32 v2, v7, v2, s6
	ds_write_b16_d16_hi v1, v2 offset:35088
	v_bfe_u32 v2, v8, 16, 1
	v_add3_u32 v2, v8, v2, s6
	ds_write_b16_d16_hi v1, v2 offset:37152
	v_bfe_u32 v2, v9, 16, 1
	v_add3_u32 v2, v9, v2, s6
	ds_write_b16_d16_hi v1, v2 offset:39216
	s_waitcnt vmcnt(17)
	v_bfe_u32 v2, v18, 16, 1
	v_add3_u32 v2, v18, v2, s6
	ds_write_b16_d16_hi v1, v2 offset:41280
	v_bfe_u32 v2, v19, 16, 1
	v_add3_u32 v2, v19, v2, s6
	ds_write_b16_d16_hi v1, v2 offset:43344
	v_bfe_u32 v2, v20, 16, 1
	v_add3_u32 v2, v20, v2, s6
	ds_write_b16_d16_hi v1, v2 offset:45408
	v_bfe_u32 v2, v21, 16, 1
	v_add3_u32 v2, v21, v2, s6
	ds_write_b16_d16_hi v1, v2 offset:47472
	v_bfe_u32 v2, v14, 16, 1
	v_add3_u32 v2, v14, v2, s6
	ds_write_b16_d16_hi v1, v2 offset:49536
	v_bfe_u32 v2, v15, 16, 1
	v_add3_u32 v2, v15, v2, s6
	ds_write_b16_d16_hi v1, v2 offset:51600
	v_bfe_u32 v2, v16, 16, 1
	v_add3_u32 v2, v16, v2, s6
	ds_write_b16_d16_hi v1, v2 offset:53664
	v_bfe_u32 v2, v17, 16, 1
	v_add3_u32 v2, v17, v2, s6
	ds_write_b16_d16_hi v1, v2 offset:55728
	v_bfe_u32 v2, v10, 16, 1
	v_add3_u32 v2, v10, v2, s6
	ds_write_b16_d16_hi v1, v2 offset:57792
	v_bfe_u32 v2, v11, 16, 1
	v_add3_u32 v2, v11, v2, s6
	ds_write_b16_d16_hi v1, v2 offset:59856
	v_bfe_u32 v2, v12, 16, 1
	v_add3_u32 v2, v12, v2, s6
	ds_write_b16_d16_hi v1, v2 offset:61920
	v_bfe_u32 v2, v13, 16, 1
	v_add3_u32 v2, v13, v2, s6
	s_movk_i32 s0, 0x50
	ds_write_b16_d16_hi v1, v2 offset:63984
	v_mad_u32_u24 v1, v0, s0, 0
	s_waitcnt vmcnt(15)
	v_cvt_pk_bf16_f32 v2, v25, v26
	s_waitcnt vmcnt(13)
	v_cvt_pk_bf16_f32 v3, v27, v28
	v_add_u32_e32 v1, 0x10200, v1
	v_cndmask_b32_e64 v5, v3, 0, vcc
	v_cndmask_b32_e64 v4, v2, 0, vcc
	v_cndmask_b32_e32 v3, 0, v3, vcc
	v_cndmask_b32_e32 v2, 0, v2, vcc
	ds_write_b128 v1, v[2:5]
	s_waitcnt vmcnt(11)
	v_cvt_pk_bf16_f32 v2, v29, v30
	v_cndmask_b32_e64 v4, v2, 0, vcc
	s_waitcnt vmcnt(9)
	v_cvt_pk_bf16_f32 v3, v31, v32
	v_cndmask_b32_e64 v5, v3, 0, vcc
	v_cndmask_b32_e32 v3, 0, v3, vcc
	v_cndmask_b32_e32 v2, 0, v2, vcc
	ds_write_b128 v1, v[2:5] offset:16
	s_waitcnt vmcnt(7)
	v_cvt_pk_bf16_f32 v2, v33, v36
	s_waitcnt vmcnt(5)
	v_cvt_pk_bf16_f32 v3, v37, v38
	v_cndmask_b32_e64 v5, v3, 0, vcc
	v_cndmask_b32_e64 v4, v2, 0, vcc
	v_cndmask_b32_e32 v3, 0, v3, vcc
	v_cndmask_b32_e32 v2, 0, v2, vcc
	ds_write_b128 v1, v[2:5] offset:32
	s_waitcnt vmcnt(3)
	v_cvt_pk_bf16_f32 v2, v22, v23
	s_waitcnt vmcnt(1)
	v_cvt_pk_bf16_f32 v3, v39, v40
	v_cndmask_b32_e64 v5, v3, 0, vcc
	v_cndmask_b32_e64 v4, v2, 0, vcc
	v_cndmask_b32_e32 v3, 0, v3, vcc
	v_cndmask_b32_e32 v2, 0, v2, vcc
	ds_write_b128 v1, v[2:5] offset:48
	v_add_u32_e32 v1, 0x1a200, v149
	s_waitcnt vmcnt(0)
	ds_write_b32 v1, v34
	s_waitcnt lgkmcnt(0)
	s_barrier
	s_cbranch_scc0 .LBB0_29
	v_and_b32_e32 v1, 15, v0
	v_lshl_or_b32 v2, s80, 4, v1
	v_ashrrev_i32_e32 v3, 31, v2
	v_lshrrev_b32_e32 v34, 4, v148
	v_lshlrev_b64 v[2:3], 12, v[2:3]
	v_lshl_add_u64 v[2:3], s[36:37], 0, v[2:3]
	v_lshlrev_b32_e32 v36, 5, v34
	v_mov_b32_e32 v37, v35
	v_lshl_add_u64 v[38:39], v[2:3], 0, v[36:37]
	global_load_dwordx4 v[6:9], v[38:39], off nt
	global_load_dwordx4 v[14:17], v[38:39], off offset:16 nt
	global_load_dwordx4 v[10:13], v[38:39], off offset:128 nt
	global_load_dwordx4 v[22:25], v[38:39], off offset:144 nt
	global_load_dwordx4 v[18:21], v[38:39], off offset:256 nt
	global_load_dwordx4 v[30:33], v[38:39], off offset:272 nt
	global_load_dwordx4 v[26:29], v[38:39], off offset:384 nt
	global_load_dwordx4 v[2:5], v[38:39], off offset:400 nt
	v_lshl_add_u64 v[44:45], s[36:37], 0, v[36:37]
	v_lshlrev_b32_e32 v36, 1, v0
	v_mul_u32_u24_e32 v39, 0x810, v1
	v_and_b32_e32 v36, 0x60, v36
	v_and_b32_e32 v58, 48, v148
	v_and_b32_e32 v38, 48, v0
	v_lshl_add_u64 v[36:37], s[36:37], 0, v[36:37]
	s_mov_b64 s[36:37], 0x400
	s_lshl_b32 s1, s2, 7
	s_lshl_b32 s4, s33, 4
	v_add3_u32 v59, v39, v58, 0
	v_mov_b32_e32 v39, v35
	v_lshlrev_b32_e32 v34, 3, v34
	v_lshl_add_u64 v[46:47], v[36:37], 0, s[36:37]
	s_add_i32 s1, s1, s4
	v_lshl_add_u64 v[36:37], s[34:35], 0, v[38:39]
	s_mov_b64 s[4:5], 0x340001c0
	v_or_b32_e32 v48, s1, v1
	s_lshl_b32 s41, s3, 7
	v_lshl_add_u64 v[50:51], v[36:37], 0, s[4:5]
	v_lshl_add_u64 v[52:53], s[34:35], 0, v[34:35]
	v_mad_u32_u24 v60, v1, s0, v38
	s_mov_b64 s[38:39], 0x200
	s_mov_b32 s46, 0xbfb8aa3b
	s_mov_b32 s47, 0x800000
	s_mov_b32 s52, 0xbd800000
	s_mov_b32 s53, 0x7f800000
	s_mov_b32 s40, 0x3db8aa3b
	s_brev_b32 s81, 60
	v_mov_b32_e32 v61, 0x41b17218

.LBB0_27:
	v_add_u32_e32 v42, 0, v41
	v_add_u32_e32 v43, 0, v40
	v_add_u32_e32 v49, 0x10200, v42
	v_add_u32_e32 v56, 0x1a200, v43
	v_add_u32_e32 v57, 0x10700, v42
	v_add_u32_e32 v74, 0x1a240, v43
	v_add_u32_e32 v78, 0x10c00, v42
	v_add_u32_e32 v82, 0x1a280, v43
	v_add_u32_e32 v42, 0x11100, v42
	ds_read_b128 v[62:65], v49
	ds_read_b128 v[66:69], v56
	v_add_u32_e32 v43, 0x1a2c0, v43
	ds_read_b128 v[70:73], v57
	ds_read_b128 v[74:77], v74
	ds_read_b128 v[78:81], v78
	ds_read_b128 v[82:85], v82
	ds_read_b128 v[86:89], v42
	ds_read_b128 v[90:93], v43
	s_waitcnt lgkmcnt(7)
	v_mfma_f32_16x16x32_bf16 v[62:65], v[62:65], v[34:37], 0
	v_lshl_add_u64 v[38:39], v[54:55], 0, s[44:45]
	v_add_co_u32_e32 v38, vcc, s81, v38
	s_waitcnt lgkmcnt(5)
	v_mfma_f32_16x16x32_bf16 v[70:73], v[70:73], v[34:37], 0
	v_addc_co_u32_e32 v39, vcc, 0, v39, vcc
	s_nop 2
	v_add_f32_e32 v43, v62, v66
	s_waitcnt lgkmcnt(3)
	v_mfma_f32_16x16x32_bf16 v[78:81], v[78:81], v[34:37], 0
	v_add_f32_e32 v49, v63, v67
	v_add_f32_e32 v57, v64, v68
	v_add_f32_e32 v62, v65, v69
	s_waitcnt lgkmcnt(1)
	v_mfma_f32_16x16x32_bf16 v[86:89], v[86:89], v[34:37], 0
	v_add_f32_e32 v63, v70, v74
	v_add_f32_e32 v64, v71, v75
	v_add_f32_e32 v65, v72, v76
	v_add_f32_e32 v66, v73, v77
	v_add_f32_e32 v67, v78, v82
	v_add_f32_e32 v68, v79, v83
	v_add_f32_e32 v69, v80, v84
	v_add_f32_e32 v70, v81, v85
	s_waitcnt lgkmcnt(0)
	v_add_f32_e32 v71, v86, v90
	v_add_f32_e32 v72, v87, v91
	v_add_f32_e32 v73, v88, v92
	v_add_f32_e32 v74, v89, v93
	v_min_f32_e32 v42, 0, v43
	v_mul_f32_e64 v75, |v43|, s46
	v_min_f32_e32 v43, 0, v49
	v_mul_f32_e64 v49, |v49|, s46
	v_mul_f32_e64 v76, |v57|, s46
	v_mul_f32_e64 v77, |v62|, s46
	v_min_f32_e32 v56, 0, v57
	v_min_f32_e32 v57, 0, v62
	v_min_f32_e32 v62, 0, v63
	v_mul_f32_e64 v78, |v63|, s46
	v_min_f32_e32 v63, 0, v64
	v_mul_f32_e64 v79, |v64|, s46
	v_min_f32_e32 v64, 0, v65
	v_mul_f32_e64 v80, |v65|, s46
	v_min_f32_e32 v65, 0, v66
	v_mul_f32_e64 v81, |v66|, s46
	v_min_f32_e32 v66, 0, v67
	v_mul_f32_e64 v82, |v67|, s46
	v_min_f32_e32 v67, 0, v68
	v_mul_f32_e64 v83, |v68|, s46
	v_min_f32_e32 v68, 0, v69
	v_mul_f32_e64 v84, |v69|, s46
	v_min_f32_e32 v69, 0, v70
	v_mul_f32_e64 v85, |v70|, s46
	v_min_f32_e32 v70, 0, v71
	v_mul_f32_e64 v86, |v71|, s46
	v_min_f32_e32 v71, 0, v72
	v_mul_f32_e64 v87, |v72|, s46
	v_min_f32_e32 v72, 0, v73
	v_mul_f32_e64 v88, |v73|, s46
	v_min_f32_e32 v73, 0, v74
	v_mul_f32_e64 v74, |v74|, s46
	v_exp_f32_e32 v75, v75
	v_exp_f32_e32 v49, v49
	v_exp_f32_e32 v76, v76
	v_exp_f32_e32 v77, v77
	v_exp_f32_e32 v78, v78
	v_exp_f32_e32 v79, v79
	v_exp_f32_e32 v80, v80
	v_exp_f32_e32 v81, v81
	v_exp_f32_e32 v82, v82
	v_exp_f32_e32 v83, v83
	v_exp_f32_e32 v84, v84
	v_exp_f32_e32 v85, v85
	v_exp_f32_e32 v86, v86
	v_exp_f32_e32 v87, v87
	v_exp_f32_e32 v88, v88
	v_exp_f32_e32 v74, v74
	v_add_f32_e32 v75, 1.0, v75
	v_add_f32_e32 v49, 1.0, v49
	v_add_f32_e32 v76, 1.0, v76
	v_add_f32_e32 v77, 1.0, v77
	v_add_f32_e32 v78, 1.0, v78
	v_add_f32_e32 v79, 1.0, v79
	v_add_f32_e32 v80, 1.0, v80
	v_add_f32_e32 v81, 1.0, v81
	v_add_f32_e32 v82, 1.0, v82
	v_add_f32_e32 v83, 1.0, v83
	v_add_f32_e32 v84, 1.0, v84
	v_add_f32_e32 v85, 1.0, v85
	v_add_f32_e32 v86, 1.0, v86
	v_add_f32_e32 v87, 1.0, v87
	v_add_f32_e32 v88, 1.0, v88
	v_add_f32_e32 v74, 1.0, v74
	v_log_f32_e32 v90, v75
	v_log_f32_e32 v91, v49
	v_log_f32_e32 v92, v76
	v_log_f32_e32 v93, v77
	v_log_f32_e32 v94, v78
	v_log_f32_e32 v95, v79
	v_log_f32_e32 v96, v80
	v_log_f32_e32 v97, v81
	v_log_f32_e32 v98, v82
	v_log_f32_e32 v99, v83
	v_log_f32_e32 v100, v84
	v_log_f32_e32 v101, v85
	v_log_f32_e32 v102, v86
	v_log_f32_e32 v103, v87
	v_log_f32_e32 v104, v88
	v_log_f32_e32 v105, v74
	s_add_u32 s44, s44, 0x800000
	s_addc_u32 s45, s45, 0
	v_pk_mul_f32 v[42:43], v[42:43], s[40:41] op_sel_hi:[1,0]
	v_pk_mul_f32 v[56:57], v[56:57], s[40:41] op_sel_hi:[1,0]
	v_pk_mul_f32 v[62:63], v[62:63], s[40:41] op_sel_hi:[1,0]
	v_pk_mul_f32 v[64:65], v[64:65], s[40:41] op_sel_hi:[1,0]
	v_pk_mul_f32 v[66:67], v[66:67], s[40:41] op_sel_hi:[1,0]
	v_pk_mul_f32 v[68:69], v[68:69], s[40:41] op_sel_hi:[1,0]
	v_pk_mul_f32 v[70:71], v[70:71], s[40:41] op_sel_hi:[1,0]
	v_pk_mul_f32 v[72:73], v[72:73], s[40:41] op_sel_hi:[1,0]
	v_add_u32_e32 v41, 0x1400, v41
	v_add_u32_e32 v40, 0x100, v40
	s_cmp_eq_u32 s44, 0x4000000
	v_pk_fma_f32 v[42:43], v[90:91], s[52:53], v[42:43] op_sel_hi:[1,0,1]
	v_pk_fma_f32 v[56:57], v[92:93], s[52:53], v[56:57] op_sel_hi:[1,0,1]
	v_pk_fma_f32 v[62:63], v[94:95], s[52:53], v[62:63] op_sel_hi:[1,0,1]
	v_pk_fma_f32 v[64:65], v[96:97], s[52:53], v[64:65] op_sel_hi:[1,0,1]
	v_pk_fma_f32 v[66:67], v[98:99], s[52:53], v[66:67] op_sel_hi:[1,0,1]
	v_pk_fma_f32 v[68:69], v[100:101], s[52:53], v[68:69] op_sel_hi:[1,0,1]
	v_pk_fma_f32 v[70:71], v[102:103], s[52:53], v[70:71] op_sel_hi:[1,0,1]
	v_pk_fma_f32 v[72:73], v[104:105], s[52:53], v[72:73] op_sel_hi:[1,0,1]
	v_cvt_pk_bf16_f32 v42, v42, v43
	v_cvt_pk_bf16_f32 v43, v56, v57
	v_cvt_pk_bf16_f32 v56, v62, v63
	v_cvt_pk_bf16_f32 v57, v64, v65
	v_cvt_pk_bf16_f32 v62, v66, v67
	v_cvt_pk_bf16_f32 v63, v68, v69
	v_cvt_pk_bf16_f32 v64, v70, v71
	v_cvt_pk_bf16_f32 v65, v72, v73
	global_store_dwordx2 v[38:39], v[42:43], off
	global_store_dwordx2 v[38:39], v[56:57], off offset:32
	global_store_dwordx2 v[38:39], v[62:63], off offset:64
	global_store_dwordx2 v[38:39], v[64:65], off offset:96
	s_cbranch_scc0 .LBB0_27
	v_add_u32_e32 v48, s41, v48
	s_and_b64 vcc, exec, s[42:43]
	s_cbranch_vccz .LBB0_24

.LBB0_161:
	v_lshrrev_b32_e32 v26, 1, v12
	v_lshrrev_b32_e32 v27, 1, v13
	v_lshrrev_b32_e32 v28, 1, v14
	v_lshrrev_b32_e32 v29, 1, v15
	v_and_b32_e32 v29, 12, v29
	v_and_b32_e32 v28, 12, v28
	v_and_b32_e32 v27, 12, v27
	v_and_b32_e32 v26, 12, v26
	v_or_b32_e32 v42, v26, v4
	v_or_b32_e32 v43, v27, v5
	v_or_b32_e32 v44, v28, v8
	v_or_b32_e32 v45, v29, v7
	v_add_u32_e32 v26, v6, v26
	v_add_u32_e32 v27, v9, v27
	v_add_u32_e32 v28, v10, v28
	v_add_u32_e32 v29, v11, v29
	v_and_b32_e32 v30, 0x60, v15
	v_and_b32_e32 v31, 0x60, v14
	v_and_b32_e32 v32, 0x60, v13
	v_and_b32_e32 v33, 0x60, v12
	v_cndmask_b32_e32 v29, v29, v45, vcc
	v_cndmask_b32_e32 v28, v28, v44, vcc
	v_cndmask_b32_e32 v27, v27, v43, vcc
	v_cndmask_b32_e32 v26, v26, v42, vcc
	v_lshrrev_b32_e32 v1, 7, v12
	v_lshrrev_b32_e32 v2, 7, v13
	v_lshrrev_b32_e32 v3, 7, v14
	v_lshrrev_b32_e32 v25, 7, v15
	v_add_u32_e32 v52, v26, v33
	v_add_u32_e32 v53, v27, v32
	v_add_u32_e32 v54, v28, v31
	v_add_u32_e32 v55, v29, v30
	v_mul_lo_u32 v38, v25, s23
	v_mul_lo_u32 v39, v3, s23
	v_mul_lo_u32 v40, v2, s23
	v_mul_lo_u32 v41, v1, s23
	v_mul_lo_u32 v25, v55, v25
	v_mul_lo_u32 v3, v54, v3
	v_mul_lo_u32 v2, v53, v2
	v_mul_lo_u32 v1, v52, v1
	v_and_b32_e32 v1, 63, v1
	v_and_b32_e32 v26, 63, v2
	v_and_b32_e32 v2, 63, v3
	v_and_b32_e32 v3, 63, v25
	v_cvt_f32_ubyte0_e32 v3, v3
	v_cvt_f32_ubyte0_e32 v2, v2
	v_cvt_f32_ubyte0_e32 v27, v26
	v_cvt_f32_ubyte0_e32 v26, v1
	v_lshlrev_b32_e32 v34, 1, v12
	v_lshlrev_b32_e32 v35, 1, v13
	v_pk_mul_f32 v[26:27], v[26:27], s[14:15] op_sel_hi:[1,0]
	v_pk_mul_f32 v[2:3], v[2:3], s[14:15] op_sel_hi:[1,0]
	v_add_u32_e32 v23, -4, v23
	v_and_b32_e32 v35, 0xfe, v35
	v_and_b32_e32 v34, 0xfe, v34
	v_pk_mul_f32 v[28:29], v[2:3], 0.5 op_sel_hi:[1,0]
	v_pk_mul_f32 v[30:31], v[26:27], 0.5 op_sel_hi:[1,0]
	v_cmp_eq_u32_e64 s[4:5], 0, v23
	v_bfe_u32 v62, v12, 7, 4
	v_add_u32_e32 v62, 4, v62
	v_bfe_u32 v62, v62, 3, 1
	v_lshlrev_b32_e32 v62, 4, v62
	v_xor_b32_e32 v34, v34, v62
	v_bfe_u32 v62, v13, 7, 4
	v_add_u32_e32 v62, 4, v62
	v_bfe_u32 v62, v62, 3, 1
	v_lshlrev_b32_e32 v62, 4, v62
	v_xor_b32_e32 v35, v35, v62
	v_add3_u32 v48, 0, v41, v34
	v_add3_u32 v49, 0, v40, v35
	v_fract_f32_e32 v32, v30
	v_fract_f32_e32 v33, v31
	v_fract_f32_e32 v34, v28
	v_fract_f32_e32 v35, v29
	s_or_b64 s[12:13], s[4:5], s[12:13]
	v_pk_add_f32 v[34:35], v[34:35], v[34:35]
	v_pk_add_f32 v[32:33], v[32:33], v[32:33]
	v_cmp_neq_f32_e64 s[4:5], s15, v31
	v_cmp_neq_f32_e64 s[6:7], s15, v28
	v_cmp_neq_f32_e64 s[8:9], s15, v29
	v_cmp_neq_f32_e64 s[10:11], s15, v30
	v_cndmask_b32_e64 v25, 0, v33, s[4:5]
	v_cndmask_b32_e64 v28, 0, v34, s[6:7]
	v_cndmask_b32_e64 v1, 0, v32, s[10:11]
	v_cndmask_b32_e64 v29, 0, v35, s[8:9]
	v_cmp_lt_f32_e64 s[4:5], 1.0, v26
	v_cmp_lt_f32_e64 s[6:7], 1.0, v27
	v_cmp_lt_f32_e64 s[8:9], 1.0, v2
	v_cmp_lt_f32_e64 s[10:11], 1.0, v3
	v_cndmask_b32_e64 v31, v27, v25, s[6:7]
	v_cndmask_b32_e64 v28, v2, v28, s[8:9]
	v_cndmask_b32_e64 v29, v3, v29, s[10:11]
	v_cndmask_b32_e64 v30, v26, v1, s[4:5]
	v_pk_add_f32 v[32:33], v[30:31], v[30:31]
	v_pk_add_f32 v[34:35], v[28:29], v[28:29]
	v_rndne_f32_e32 v33, v33
	v_rndne_f32_e32 v35, v35
	v_rndne_f32_e32 v34, v34
	v_rndne_f32_e32 v32, v32
	v_lshlrev_b32_e32 v36, 1, v14
	v_lshlrev_b32_e32 v37, 1, v15
	v_pk_fma_f32 v[30:31], v[32:33], -0.5, v[30:31] op_sel_hi:[1,0,1]
	v_pk_fma_f32 v[28:29], v[34:35], -0.5, v[28:29] op_sel_hi:[1,0,1]
	v_and_b32_e32 v37, 0xfe, v37
	v_and_b32_e32 v36, 0xfe, v36
	v_cvt_i32_f32_e32 v1, v35
	v_cvt_i32_f32_e32 v25, v34
	v_cvt_i32_f32_e32 v56, v33
	v_cvt_i32_f32_e32 v57, v32
	v_pk_mul_f32 v[32:33], v[28:29], v[28:29]
	v_pk_mul_f32 v[34:35], v[30:31], v[30:31]
	v_bfe_u32 v62, v14, 7, 4
	v_add_u32_e32 v62, 4, v62
	v_bfe_u32 v62, v62, 3, 1
	v_lshlrev_b32_e32 v62, 4, v62
	v_xor_b32_e32 v36, v36, v62
	v_bfe_u32 v62, v15, 7, 4
	v_add_u32_e32 v62, 4, v62
	v_bfe_u32 v62, v62, 3, 1
	v_lshlrev_b32_e32 v62, 4, v62
	v_xor_b32_e32 v37, v37, v62
	v_add3_u32 v50, 0, v39, v36
	v_add3_u32 v51, 0, v38, v37
	v_pk_fma_f32 v[36:37], v[34:35], s[18:19], v[16:17] op_sel_hi:[1,0,0]
	v_pk_fma_f32 v[38:39], v[32:33], s[18:19], v[16:17] op_sel_hi:[1,0,0]
	v_pk_fma_f32 v[44:45], v[34:35], s[28:29], v[18:19] op_sel_hi:[1,0,0]
	v_pk_fma_f32 v[46:47], v[32:33], s[28:29], v[18:19] op_sel_hi:[1,0,0]
	v_pk_fma_f32 v[38:39], v[32:33], v[38:39], s[22:23] op_sel_hi:[1,1,0]
	v_pk_fma_f32 v[36:37], v[34:35], v[36:37], s[22:23] op_sel_hi:[1,1,0]
	v_pk_fma_f32 v[46:47], v[32:33], v[46:47], s[30:31] op_sel_hi:[1,1,0]
	v_pk_fma_f32 v[44:45], v[34:35], v[44:45], s[30:31] op_sel_hi:[1,1,0]
	v_pk_mul_f32 v[40:41], v[30:31], v[34:35]
	v_pk_mul_f32 v[42:43], v[28:29], v[32:33]
	v_pk_fma_f32 v[36:37], v[34:35], v[36:37], s[24:25] op_sel_hi:[1,1,0]
	v_pk_fma_f32 v[38:39], v[32:33], v[38:39], s[24:25] op_sel_hi:[1,1,0]
	v_pk_fma_f32 v[44:45], v[34:35], v[44:45], s[36:37] op_sel_hi:[1,1,0]
	v_pk_fma_f32 v[46:47], v[32:33], v[46:47], s[36:37] op_sel_hi:[1,1,0]
	v_lshlrev_b32_e32 v58, 30, v57
	v_lshlrev_b32_e32 v61, 30, v1
	v_and_b32_e32 v1, 1, v1
	v_and_b32_e32 v57, 1, v57
	v_pk_mul_f32 v[38:39], v[42:43], v[38:39]
	v_pk_mul_f32 v[36:37], v[40:41], v[36:37]
	v_pk_fma_f32 v[40:41], v[32:33], v[46:47], s[38:39] op_sel_hi:[1,1,0]
	v_pk_fma_f32 v[42:43], v[34:35], v[44:45], s[38:39] op_sel_hi:[1,1,0]
	v_lshlrev_b32_e32 v59, 30, v56
	v_lshlrev_b32_e32 v60, 30, v25
	v_and_b32_e32 v25, 1, v25
	v_and_b32_e32 v56, 1, v56
	v_pk_fma_f32 v[30:31], v[30:31], s[26:27], v[36:37] op_sel_hi:[1,0,1]
	v_pk_fma_f32 v[28:29], v[28:29], s[26:27], v[38:39] op_sel_hi:[1,0,1]
	v_pk_fma_f32 v[34:35], v[34:35], v[42:43], 1.0 op_sel_hi:[1,1,0]
	v_pk_fma_f32 v[32:33], v[32:33], v[40:41], 1.0 op_sel_hi:[1,1,0]
	v_cmp_eq_u32_e64 s[4:5], 0, v57
	v_cmp_eq_u32_e64 s[10:11], 0, v1
	v_and_b32_e32 v44, 0x80000000, v61
	v_and_b32_e32 v47, 0x80000000, v58
	v_cmp_eq_u32_e64 s[6:7], 0, v56
	v_cmp_eq_u32_e64 s[8:9], 0, v25
	v_cndmask_b32_e64 v1, v33, v29, s[10:11]
	v_cndmask_b32_e64 v37, v34, v30, s[4:5]
	v_cndmask_b32_e64 v29, -v29, v33, s[10:11]
	v_cndmask_b32_e64 v30, -v30, v34, s[4:5]
	v_and_b32_e32 v45, 0x80000000, v60
	v_and_b32_e32 v46, 0x80000000, v59
	v_cndmask_b32_e64 v25, v32, v28, s[8:9]
	v_cndmask_b32_e64 v36, v35, v31, s[6:7]
	v_cndmask_b32_e64 v28, -v28, v32, s[8:9]
	v_cndmask_b32_e64 v31, -v31, v35, s[6:7]
	v_xor_b32_e32 v29, v44, v29
	v_cmp_lg_f32_e64 s[4:5], s15, v3
	v_cmp_lg_f32_e64 s[8:9], s15, v27
	v_xor_b32_e32 v27, v47, v30
	v_xor_b32_e32 v30, v47, v37
	v_xor_b32_e32 v1, v44, v1
	v_cmp_lg_f32_e64 s[10:11], s15, v26
	v_xor_b32_e32 v3, v45, v28
	v_cmp_lg_f32_e64 s[6:7], s15, v2
	v_xor_b32_e32 v2, v46, v31
	v_xor_b32_e32 v28, v46, v36
	v_xor_b32_e32 v25, v45, v25
	v_cndmask_b32_e64 v26, v24, v27, s[10:11]
	v_cndmask_b32_e64 v27, v24, v29, s[4:5]
	v_cndmask_b32_e64 v29, v24, v30, s[10:11]
	v_cndmask_b32_e64 v1, v24, v1, s[4:5]
	v_cmp_gt_u32_e64 s[4:5], 64, v52
	v_cmp_gt_u32_e64 s[10:11], 64, v55
	v_cndmask_b32_e64 v2, v24, v2, s[8:9]
	v_cndmask_b32_e64 v3, v24, v3, s[6:7]
	v_cndmask_b32_e64 v28, v24, v28, s[8:9]
	v_cndmask_b32_e64 v25, v24, v25, s[6:7]
	v_cmp_gt_u32_e64 s[6:7], 64, v53
	v_cmp_gt_u32_e64 s[8:9], 64, v54
	v_cndmask_b32_e64 v30, -v1, v27, s[10:11]
	v_cndmask_b32_e64 v33, -v29, v26, s[4:5]
	v_cndmask_b32_e64 v26, v26, v29, s[4:5]
	v_cndmask_b32_e64 v31, -v25, v3, s[8:9]
	v_cndmask_b32_e64 v32, -v28, v2, s[6:7]
	v_cndmask_b32_e64 v2, v2, v28, s[6:7]
	v_cndmask_b32_e64 v3, v3, v25, s[8:9]
	v_cndmask_b32_e64 v1, v27, v1, s[10:11]
	v_xor_b32_e32 v25, 0x80000000, v26
	v_bfe_u32 v29, v30, 16, 1
	v_xor_b32_e32 v1, 0x80000000, v1
	v_xor_b32_e32 v3, 0x80000000, v3
	v_xor_b32_e32 v2, 0x80000000, v2
	v_bfe_u32 v26, v33, 16, 1
	v_bfe_u32 v27, v32, 16, 1
	v_bfe_u32 v28, v31, 16, 1
	v_add3_u32 v29, v30, v29, s19
	v_bfe_u32 v30, v25, 16, 1
	v_add_u32_e32 v15, 0x800, v15
	v_add_u32_e32 v14, 0x800, v14
	v_add_u32_e32 v13, 0x800, v13
	v_add_u32_e32 v12, 0x800, v12
	v_add3_u32 v28, v31, v28, s19
	v_add3_u32 v27, v32, v27, s19
	v_add3_u32 v26, v33, v26, s19
	v_bfe_u32 v31, v2, 16, 1
	v_bfe_u32 v32, v3, 16, 1
	v_bfe_u32 v33, v1, 16, 1
	v_add3_u32 v25, v25, v30, s19
	ds_write_b16_d16_hi v48, v26 offset:34816
	ds_write_b16_d16_hi v49, v27 offset:34816
	ds_write_b16_d16_hi v50, v28 offset:34816
	ds_write_b16_d16_hi v51, v29 offset:34816
	v_add3_u32 v1, v1, v33, s19
	v_add3_u32 v3, v3, v32, s19
	v_add3_u32 v2, v2, v31, s19
	ds_write_b16_d16_hi v48, v25 offset:52224
	ds_write_b16_d16_hi v49, v2 offset:52224
	ds_write_b16_d16_hi v50, v3 offset:52224
	ds_write_b16_d16_hi v51, v1 offset:52224
	s_andn2_b64 exec, exec, s[12:13]
	s_cbranch_execnz .LBB0_161
	s_or_b64 exec, exec, s[12:13]
	v_cmp_ne_u32_e64 s[4:5], 16, 16
	s_and_saveexec_b64 s[6:7], s[4:5]
	s_cbranch_execz .LBB0_165
	v_lshl_or_b32 v7, 16, 9, v0
	v_mov_b32_e32 v2, 0x4000
	v_lshlrev_b32_e32 v3, 1, v0
	s_movk_i32 s4, 0x7000
	v_lshrrev_b32_e32 v1, 7, v7
	v_and_or_b32 v2, v2, s4, v3
	v_lshrrev_b16_e32 v3, 1, v7
	s_mov_b64 s[8:9], 0
	s_mov_b32 s10, 0x7f800000
	v_mov_b32_e32 v5, 0xbf1f24be
	v_mov_b32_e32 v8, 0x3e642e9d
	s_brev_b32 s11, 1
	v_mov_b32_e32 v9, 0x7fc00000
	s_movk_i32 s12, 0x7fff
	s_movk_i32 s13, 0x1dff

.LBB0_211:
	s_add_u32 s8, s34, 0xa84000
	s_addc_u32 s9, s35, 0
	s_add_u32 s10, s34, 0xa80000
	s_addc_u32 s11, s35, 0
	s_lshl_b32 s26, s2, 5
	s_lshr_b32 s1, s2, 1
	s_waitcnt vmcnt(0)
	v_lshrrev_b32_e32 v23, 4, v0
	v_bfe_u32 v25, v0, 3, 1
	s_and_b32 s0, s26, 0xfffff000
	s_and_b32 s1, s1, 62
	s_or_b32 s4, s0, s1
	s_lshl_b32 s0, s2, 24
	v_lshl_or_b32 v127, v23, 6, v25
	s_and_b32 s0, s0, 0x3000000
	v_or_b32_e32 v2, s4, v127
	s_add_u32 s5, s20, s0
	v_ashrrev_i32_e32 v3, 31, v2
	s_addc_u32 s18, s21, 0
	v_lshlrev_b64 v[10:11], 7, v[2:3]
	v_or_b32_e32 v2, 0x800, v2
	s_add_u32 s0, s5, 0xc000000
	v_ashrrev_i32_e32 v3, 31, v2
	s_addc_u32 s1, s18, 0
	v_lshlrev_b64 v[14:15], 7, v[2:3]
	v_lshl_add_u64 v[4:5], s[0:1], 0, v[10:11]
	v_lshl_add_u64 v[2:3], s[0:1], 0, v[14:15]
	s_add_u32 s0, s5, 0xc800000
	v_and_b32_e32 v22, 7, v0
	s_addc_u32 s1, s18, 0
	v_mov_b32_e32 v69, 0
	v_lshlrev_b32_e32 v68, 4, v22
	v_lshl_add_u64 v[10:11], s[0:1], 0, v[10:11]
	v_lshl_add_u64 v[12:13], v[4:5], 0, v[68:69]
	v_lshl_add_u64 v[16:17], v[2:3], 0, v[68:69]
	v_lshl_add_u64 v[18:19], v[10:11], 0, v[68:69]
	v_lshl_add_u64 v[10:11], s[0:1], 0, v[14:15]
	global_load_dwordx4 v[2:5], v[12:13], off
	global_load_dwordx4 v[6:9], v[16:17], off
	v_lshl_add_u64 v[20:21], v[10:11], 0, v[68:69]
	global_load_dwordx4 v[10:13], v[18:19], off
	global_load_dwordx4 v[14:17], v[20:21], off
	s_lshl_b32 s4, s33, 6
	s_add_u32 s0, s70, s4
	s_addc_u32 s1, s71, 0
	v_lshlrev_b32_e32 v72, 2, v126
	v_mov_b32_e32 v73, v69
	v_lshlrev_b32_e32 v20, 10, v67
	v_and_b32_e32 v19, 48, v0
	v_lshl_or_b32 v21, v25, 6, v23
	s_movk_i32 s27, 0x110
	v_lshl_add_u64 v[70:71], s[0:1], 0, v[72:73]
	s_add_u32 s0, s68, s4
	v_mul_u32_u24_e32 v23, 0x110, v126
	v_lshlrev_b32_e32 v18, 3, v22
	v_add_u32_e32 v128, 0, v19
	v_lshlrev_b32_e32 v66, 2, v67
	v_or_b32_e32 v22, 0x3000, v20
	v_or_b32_e32 v24, 0x1000, v20
	v_or_b32_e32 v26, 0x1080, v20
	v_or_b32_e32 v28, 0x1100, v20
	v_or_b32_e32 v30, 0x1180, v20
	v_or_b32_e32 v32, 0x1200, v20
	v_or_b32_e32 v34, 0x1280, v20
	v_or_b32_e32 v36, 0x1300, v20
	v_or_b32_e32 v38, 0x1380, v20
	v_or_b32_e32 v40, 0x2000, v20
	v_or_b32_e32 v42, 0x2080, v20
	v_or_b32_e32 v44, 0x2100, v20
	v_or_b32_e32 v46, 0x2180, v20
	v_or_b32_e32 v48, 0x2200, v20
	v_or_b32_e32 v50, 0x2280, v20
	v_or_b32_e32 v52, 0x2300, v20
	v_or_b32_e32 v54, 0x2380, v20
	v_or_b32_e32 v56, 0x3080, v20
	v_or_b32_e32 v58, 0x3100, v20
	v_or_b32_e32 v60, 0x3180, v20
	v_or_b32_e32 v62, 0x3200, v20
	v_or_b32_e32 v64, 0x3280, v20
	v_or_b32_e32 v120, 0x3300, v20
	v_or_b32_e32 v122, 0x3380, v20
	v_mad_u32_u24 v21, v21, s27, 0
	s_addc_u32 s1, s69, 0
	v_add3_u32 v19, v23, v19, 0
	v_lshrrev_b32_e32 v1, 3, v0
	s_mov_b32 s19, 0
	v_lshlrev_b32_e32 v129, 6, v126
	v_lshl_or_b32 v130, s33, 4, v66
	v_lshl_add_u64 v[72:73], s[0:1], 0, v[72:73]
	s_lshl_b32 s28, s3, 5
	v_add_u32_e32 v131, 0x8800, v19
	v_add_u32_e32 v201, 4, v126
	v_bfe_u32 v201, v201, 3, 1
	v_sub_u32_e32 v201, 0, v201
	v_bfe_u32 v202, v0, 4, 1
	v_lshlrev_b32_e32 v202, 5, v202
	v_sub_u32_e32 v202, 16, v202
	v_and_b32_e32 v201, v201, v202
	v_add_u32_e32 v128, v128, v201
	v_add_u32_e32 v131, v131, v201
	s_mov_b32 s18, -1
	v_lshlrev_b32_e32 v74, 2, v20
	s_movk_i32 s29, 0x7fff
	s_mov_b32 s30, 0x7060302
	v_lshlrev_b32_e32 v76, 2, v24
	v_lshlrev_b32_e32 v78, 2, v26
	v_lshlrev_b32_e32 v80, 2, v28
	v_lshlrev_b32_e32 v82, 2, v30
	v_lshlrev_b32_e32 v84, 2, v32
	v_lshlrev_b32_e32 v86, 2, v34
	v_lshlrev_b32_e32 v88, 2, v36
	v_lshlrev_b32_e32 v90, 2, v38
	v_lshlrev_b32_e32 v92, 2, v40
	v_lshlrev_b32_e32 v94, 2, v42
	v_lshlrev_b32_e32 v96, 2, v44
	v_lshlrev_b32_e32 v98, 2, v46
	v_lshlrev_b32_e32 v100, 2, v48
	v_lshlrev_b32_e32 v102, 2, v50
	v_lshlrev_b32_e32 v104, 2, v52
	v_lshlrev_b32_e32 v106, 2, v54
	v_lshlrev_b32_e32 v108, 2, v22
	v_lshlrev_b32_e32 v110, 2, v56
	v_lshlrev_b32_e32 v112, 2, v58
	v_lshlrev_b32_e32 v114, 2, v60
	v_lshlrev_b32_e32 v116, 2, v62
	v_lshlrev_b32_e32 v118, 2, v64
	v_lshlrev_b32_e32 v120, 2, v120
	v_lshlrev_b32_e32 v122, 2, v122
	v_add_u32_e32 v132, v21, v68
	v_bfe_u32 v201, v0, 4, 4
	v_add_u32_e32 v201, 4, v201
	v_bfe_u32 v201, v201, 3, 1
	v_sub_u32_e32 v201, 0, v201
	v_and_b32_e32 v202, 1, v0
	v_lshlrev_b32_e32 v202, 5, v202
	v_sub_u32_e32 v202, 16, v202
	v_and_b32_e32 v201, v201, v202
	v_add_u32_e32 v132, v132, v201
	v_lshlrev_b32_e32 v124, 1, v18
	s_mov_b32 s1, s2
	v_lshl_add_u32 v178, s33, 3, v67
	v_lshlrev_b32_e32 v179, 3, v126
	v_mul_u32_u24_e32 v177, 0x110, v178
	v_lshl_add_u32 v177, v126, 4, v177
	v_add_u32_e32 v177, 0x11000, v177
	v_mul_u32_u24_e32 v176, 0x110, v126
	v_lshl_add_u32 v176, s33, 5, v176
	v_lshl_add_u32 v176, v67, 3, v176
	v_add_u32_e32 v176, 0xff00, v176
	v_sub_u32_e32 v176, v176, v131

.LBB0_215:
	v_lshl_or_b32 v50, s4, 6, v126
	s_mul_i32 s7, s4, 0x8800
	s_mul_i32 s37, s4, 0xfffe2400
	s_add_i32 s37, s37, 0x4400
	v_add_u32_e32 v203, s7, v176
	v_add_u32_e32 v204, s7, v177
	v_add_u32_e32 v206, s37, v204
	v_mad_u32_u24 v109, v50, s27, v128
	ds_read_b128 v[134:137], v109
	ds_read_b128 v[138:141], v109 offset:4352
	ds_read_b128 v[142:145], v109 offset:8704
	ds_read_b128 v[150:153], v109 offset:13056
	ds_read_b128 v[154:157], v109 offset:64
	ds_read_b128 v[158:161], v109 offset:4416
	ds_read_b128 v[162:165], v109 offset:8768
	ds_read_b128 v[166:169], v109 offset:13120
	ds_read_b128 v[224:227], v109 offset:128
	ds_read_b128 v[228:231], v109 offset:4480
	ds_read_b128 v[232:235], v109 offset:8832
	ds_read_b128 v[236:239], v109 offset:13184
	s_xor_b64 s[24:25], s[0:1], -1
	v_cndmask_b32_e64 v111, v97, v81, s[0:1]
	v_cndmask_b32_e64 v113, v101, v85, s[0:1]
	v_cndmask_b32_e64 v115, v105, v89, s[0:1]
	v_cndmask_b32_e64 v117, v91, v75, s[0:1]
	v_cndmask_b32_e64 v119, v95, v79, s[0:1]
	v_cndmask_b32_e64 v121, v99, v83, s[0:1]
	v_cndmask_b32_e64 v123, v103, v87, s[0:1]
	v_add_u32_e32 v125, s4, v107
	v_mov_b32_e32 v133, v131
	s_mov_b32 s36, 0
	s_waitcnt lgkmcnt(11)
	v_mfma_f32_16x16x32_bf16 v[50:53], v[134:137], v[18:21], 0
	v_mfma_f32_16x16x32_bf16 v[58:61], v[134:137], v[34:37], 0
	s_waitcnt lgkmcnt(10)
	v_mfma_f32_16x16x32_bf16 v[208:211], v[138:141], v[18:21], 0
	v_mfma_f32_16x16x32_bf16 v[216:219], v[138:141], v[34:37], 0
	s_waitcnt lgkmcnt(9)
	v_mfma_f32_16x16x32_bf16 v[54:57], v[142:145], v[18:21], 0
	v_mfma_f32_16x16x32_bf16 v[62:65], v[142:145], v[34:37], 0
	s_waitcnt lgkmcnt(8)
	v_mfma_f32_16x16x32_bf16 v[212:215], v[150:153], v[18:21], 0
	v_mfma_f32_16x16x32_bf16 v[220:223], v[150:153], v[34:37], 0
	ds_read_b128 v[134:137], v109 offset:192
	ds_read_b128 v[138:141], v109 offset:4544
	ds_read_b128 v[142:145], v109 offset:8896
	ds_read_b128 v[150:153], v109 offset:13248
	v_cndmask_b32_e64 v109, v93, v77, s[0:1]
	s_waitcnt lgkmcnt(11)
	v_mfma_f32_16x16x32_bf16 v[50:53], v[154:157], v[22:25], v[50:53]
	v_mfma_f32_16x16x32_bf16 v[58:61], v[154:157], v[38:41], v[58:61]
	s_waitcnt lgkmcnt(10)
	v_mfma_f32_16x16x32_bf16 v[208:211], v[158:161], v[22:25], v[208:211]
	v_mfma_f32_16x16x32_bf16 v[216:219], v[158:161], v[38:41], v[216:219]
	s_waitcnt lgkmcnt(9)
	v_mfma_f32_16x16x32_bf16 v[54:57], v[162:165], v[22:25], v[54:57]
	v_mfma_f32_16x16x32_bf16 v[62:65], v[162:165], v[38:41], v[62:65]
	s_waitcnt lgkmcnt(8)
	v_mfma_f32_16x16x32_bf16 v[212:215], v[166:169], v[22:25], v[212:215]
	v_mfma_f32_16x16x32_bf16 v[220:223], v[166:169], v[38:41], v[220:223]
	s_waitcnt lgkmcnt(7)
	v_mfma_f32_16x16x32_bf16 v[50:53], v[224:227], v[26:29], v[50:53]
	v_mfma_f32_16x16x32_bf16 v[58:61], v[224:227], v[42:45], v[58:61]
	s_waitcnt lgkmcnt(6)
	v_mfma_f32_16x16x32_bf16 v[208:211], v[228:231], v[26:29], v[208:211]
	v_mfma_f32_16x16x32_bf16 v[216:219], v[228:231], v[42:45], v[216:219]
	s_waitcnt lgkmcnt(5)
	v_mfma_f32_16x16x32_bf16 v[54:57], v[232:235], v[26:29], v[54:57]
	v_mfma_f32_16x16x32_bf16 v[62:65], v[232:235], v[42:45], v[62:65]
	s_waitcnt lgkmcnt(4)
	v_mfma_f32_16x16x32_bf16 v[212:215], v[236:239], v[26:29], v[212:215]
	v_mfma_f32_16x16x32_bf16 v[220:223], v[236:239], v[42:45], v[220:223]
	s_waitcnt lgkmcnt(3)
	v_mfma_f32_16x16x32_bf16 v[50:53], v[134:137], v[30:33], v[50:53]
	v_mfma_f32_16x16x32_bf16 v[58:61], v[134:137], v[46:49], v[58:61]
	s_waitcnt lgkmcnt(2)
	v_mfma_f32_16x16x32_bf16 v[208:211], v[138:141], v[30:33], v[208:211]
	v_mfma_f32_16x16x32_bf16 v[216:219], v[138:141], v[46:49], v[216:219]
	s_waitcnt lgkmcnt(1)
	v_mfma_f32_16x16x32_bf16 v[54:57], v[142:145], v[30:33], v[54:57]
	v_mfma_f32_16x16x32_bf16 v[62:65], v[142:145], v[46:49], v[62:65]
	s_waitcnt lgkmcnt(0)
	v_mfma_f32_16x16x32_bf16 v[212:215], v[150:153], v[30:33], v[212:215]
	v_mfma_f32_16x16x32_bf16 v[220:223], v[150:153], v[46:49], v[220:223]
	s_nop 9
	v_cvt_pk_bf16_f32 v50, v50, v51
	v_cvt_pk_bf16_f32 v51, v52, v53
	v_cvt_pk_bf16_f32 v52, v208, v209
	v_cvt_pk_bf16_f32 v53, v210, v211
	v_cvt_pk_bf16_f32 v54, v54, v55
	v_cvt_pk_bf16_f32 v55, v56, v57
	v_cvt_pk_bf16_f32 v56, v212, v213
	v_cvt_pk_bf16_f32 v57, v214, v215
	v_cvt_pk_bf16_f32 v58, v58, v59
	v_cvt_pk_bf16_f32 v59, v60, v61
	v_cvt_pk_bf16_f32 v60, v216, v217
	v_cvt_pk_bf16_f32 v61, v218, v219
	v_cvt_pk_bf16_f32 v62, v62, v63
	v_cvt_pk_bf16_f32 v63, v64, v65
	v_cvt_pk_bf16_f32 v64, v220, v221
	v_cvt_pk_bf16_f32 v65, v222, v223
.LBB0_216:
	ds_read_b128 v[134:137], v133
	ds_read_b128 v[138:141], v133 offset:64
	ds_read_b128 v[142:145], v133 offset:17408
	ds_read_b128 v[150:153], v133 offset:17472
	ds_read_b128 v[154:157], v133 offset:128
	ds_read_b128 v[158:161], v133 offset:192
	ds_read_b128 v[162:165], v133 offset:17536
	ds_read_b128 v[166:169], v133 offset:17600
	s_waitcnt lgkmcnt(7)
	v_mfma_f32_16x16x32_bf16 v[134:137], v[50:53], v[134:137], 0
	s_cmp_eq_u32 s36, 0
	s_cselect_b64 vcc, -1, 0
	s_cmpk_eq_i32 s36, 0x400
	s_waitcnt lgkmcnt(5)
	v_mfma_f32_16x16x32_bf16 v[142:145], v[50:53], v[142:145], 0
	s_cselect_b64 s[0:1], -1, 0
	s_cmpk_eq_i32 s36, 0x800
	s_cselect_b64 s[4:5], -1, 0
	v_mfma_f32_16x16x32_bf16 v[134:137], v[54:57], v[138:141], v[134:137]
	v_add_u32_e32 v146, s36, v125
	v_ashrrev_i32_e32 v147, 31, v146
	v_lshlrev_b64 v[146:147], 9, v[146:147]
	s_waitcnt lgkmcnt(4)
	v_mfma_f32_16x16x32_bf16 v[138:141], v[54:57], v[150:153], v[142:145]
	s_addk_i32 s36, 0x400
	v_add_u32_e32 v133, 0x1100, v133
	s_cmpk_lg_i32 s36, 0x1000
	s_waitcnt lgkmcnt(1)
	v_mfma_f32_16x16x32_bf16 v[138:141], v[58:61], v[162:165], v[138:141]
	v_cndmask_b32_e64 v145, v123, v121, s[4:5]
	v_cndmask_b32_e64 v144, v115, v113, s[4:5]
	v_cndmask_b32_e64 v145, v145, v119, s[0:1]
	v_mfma_f32_16x16x32_bf16 v[134:137], v[58:61], v[154:157], v[134:137]
	v_cndmask_b32_e64 v144, v144, v111, s[0:1]
	v_cndmask_b32_e32 v150, v145, v117, vcc
	v_lshl_add_u64 v[142:143], v[146:147], 0, v[68:69]
	s_waitcnt lgkmcnt(0)
	v_mfma_f32_16x16x32_bf16 v[138:141], v[62:65], v[166:169], v[138:141]
	v_cndmask_b32_e32 v144, v144, v109, vcc
	v_lshlrev_b64 v[142:143], 1, v[142:143]
	v_lshl_add_u64 v[146:147], s[14:15], 0, v[142:143]
	v_mfma_f32_16x16x32_bf16 v[134:137], v[62:65], v[158:161], v[134:137]
	v_lshl_add_u64 v[142:143], s[12:13], 0, v[142:143]
	s_nop 2
	v_pk_mul_f32 v[152:153], v[150:151], v[138:139] op_sel_hi:[0,1]
	v_pk_mul_f32 v[156:157], v[150:151], v[140:141] op_sel_hi:[0,1]
	s_nop 1
	v_pk_mul_f32 v[154:155], v[150:151], v[134:135] op_sel_hi:[0,1]
	v_pk_mul_f32 v[150:151], v[150:151], v[136:137] op_sel_hi:[0,1]
	v_pk_fma_f32 v[134:135], v[144:145], v[134:135], v[152:153] op_sel_hi:[0,1,1]
	v_pk_fma_f32 v[136:137], v[144:145], v[136:137], v[156:157] op_sel_hi:[0,1,1]
	v_pk_fma_f32 v[138:139], v[144:145], v[138:139], v[154:155] op_sel_hi:[0,1,1] neg_lo:[0,0,1] neg_hi:[0,0,1]
	v_pk_fma_f32 v[140:141], v[144:145], v[140:141], v[150:151] op_sel_hi:[0,1,1] neg_lo:[0,0,1] neg_hi:[0,0,1]
	v_cvt_pk_bf16_f32 v134, v134, v135
	v_cvt_pk_bf16_f32 v135, v136, v137
	v_cvt_pk_bf16_f32 v136, v138, v139
	v_cvt_pk_bf16_f32 v137, v140, v141
	v_add_u32_e32 v200, v203, v133
	v_add_u32_e32 v205, s37, v200
	ds_write_b64 v200, v[134:135]
	ds_write_b64 v205, v[136:137]
	s_cbranch_scc1 .LBB0_216
	s_waitcnt lgkmcnt(0)
	s_barrier
	ds_read_b128 v[184:187], v204
	ds_read_b128 v[188:191], v204 offset:1088
	ds_read_b128 v[192:195], v206
	ds_read_b128 v[196:199], v206 offset:1088
	s_and_b32 s6, s24, 1
	v_add_u32_e32 v182, s6, v180
	v_lshlrev_b32_e32 v182, 10, v182
	v_lshl_add_u32 v182, v181, 1, v182
	v_add_u32_e32 v183, 0x40000, v182
	s_waitcnt lgkmcnt(0)
	global_store_dwordx4 v182, v[184:187], s[14:15]
	global_store_dwordx4 v183, v[188:191], s[14:15]
	global_store_dwordx4 v182, v[192:195], s[12:13]
	global_store_dwordx4 v183, v[196:199], s[12:13]
	s_mov_b32 s4, 1
	s_mov_b64 s[0:1], 0
	s_and_b64 vcc, exec, s[24:25]
	s_cbranch_vccz .LBB0_215
	s_add_i32 s26, s26, s28
	s_and_b64 vcc, exec, s[22:23]
	s_mov_b32 s1, s31
	s_cbranch_vccz .LBB0_212
	s_waitcnt vmcnt(5)
	v_mov_b32_e32 v2, v67
